# DA context-unit epilogue: tile staged through own LDS region, 8 full-row (4 rows x 256 B) dwordx4 stores; latent epilogue keeps permlane-widened stores
# speedup vs baseline: 1.0049x; 1.0049x over previous
.LBB0_744:
	v_mul_f32_e32 v0, v129, v129
	v_fmac_f32_e32 v0, v128, v128
	v_fmac_f32_e32 v0, v130, v130
	v_fmac_f32_e32 v0, v131, v131
	v_fmac_f32_e32 v0, v132, v132
	v_fmac_f32_e32 v0, v133, v133
	v_fmac_f32_e32 v0, v134, v134
	v_fmac_f32_e32 v0, v135, v135
	v_fmac_f32_e32 v0, v136, v136
	v_fmac_f32_e32 v0, v137, v137
	v_fmac_f32_e32 v0, v138, v138
	v_fmac_f32_e32 v0, v139, v139
	v_fmac_f32_e32 v0, v140, v140
	v_fmac_f32_e32 v0, v141, v141
	v_fmac_f32_e32 v0, v142, v142
	v_fmac_f32_e32 v0, v143, v143
	v_fmac_f32_e32 v0, v112, v112
	v_fmac_f32_e32 v0, v113, v113
	v_fmac_f32_e32 v0, v114, v114
	v_fmac_f32_e32 v0, v115, v115
	v_fmac_f32_e32 v0, v116, v116
	v_fmac_f32_e32 v0, v117, v117
	v_fmac_f32_e32 v0, v118, v118
	v_fmac_f32_e32 v0, v119, v119
	v_fmac_f32_e32 v0, v120, v120
	v_fmac_f32_e32 v0, v121, v121
	v_fmac_f32_e32 v0, v122, v122
	v_fmac_f32_e32 v0, v123, v123
	v_fmac_f32_e32 v0, v124, v124
	v_fmac_f32_e32 v0, v125, v125
	v_fmac_f32_e32 v0, v126, v126
	v_fmac_f32_e32 v0, v127, v127
	v_fmac_f32_e32 v0, v96, v96
	v_fmac_f32_e32 v0, v97, v97
	v_fmac_f32_e32 v0, v98, v98
	v_fmac_f32_e32 v0, v99, v99
	v_fmac_f32_e32 v0, v100, v100
	v_fmac_f32_e32 v0, v101, v101
	v_fmac_f32_e32 v0, v102, v102
	v_fmac_f32_e32 v0, v103, v103
	v_fmac_f32_e32 v0, v104, v104
	v_fmac_f32_e32 v0, v105, v105
	v_fmac_f32_e32 v0, v106, v106
	v_fmac_f32_e32 v0, v107, v107
	v_fmac_f32_e32 v0, v108, v108
	v_fmac_f32_e32 v0, v109, v109
	v_fmac_f32_e32 v0, v110, v110
	v_fmac_f32_e32 v0, v111, v111
	v_fmac_f32_e32 v0, v80, v80
	v_fmac_f32_e32 v0, v81, v81
	v_fmac_f32_e32 v0, v82, v82
	v_fmac_f32_e32 v0, v83, v83
	v_fmac_f32_e32 v0, v84, v84
	v_fmac_f32_e32 v0, v85, v85
	v_pk_mul_f32 v[10:11], v[86:87], v[86:87]
	v_pk_mul_f32 v[8:9], v[88:89], v[88:89]
	v_add_f32_e32 v0, v10, v0
	v_add_f32_e32 v0, v11, v0
	v_add_f32_e32 v0, v8, v0
	v_pk_mul_f32 v[6:7], v[90:91], v[90:91]
	v_add_f32_e32 v0, v9, v0
	v_add_f32_e32 v0, v6, v0
	v_pk_mul_f32 v[4:5], v[92:93], v[92:93]
	v_add_f32_e32 v0, v7, v0
	v_add_f32_e32 v0, v4, v0
	v_pk_mul_f32 v[2:3], v[94:95], v[94:95]
	v_add_f32_e32 v0, v5, v0
	v_add_f32_e32 v0, v2, v0
	v_add_f32_e32 v0, v3, v0
	ds_bpermute_b32 v2, v210, v0
	s_load_dwordx2 s[8:9], s[48:49], 0x88
	v_readlane_b32 s5, v255, 1
	s_lshl_b32 s5, s5, 2
	s_waitcnt lgkmcnt(0)
	v_add_f32_e32 v0, v0, v2
	v_fmamk_f32 v0, v0, 0x3c000000, v213
	v_cmp_gt_f32_e32 vcc, s79, v0
	v_mul_f32_e32 v2, 0x4b800000, v0
	s_add_u32 s8, s8, s5
	v_cndmask_b32_e32 v0, v0, v2, vcc
	v_rsq_f32_e32 v0, v0
	v_lshlrev_b32_e32 v10, 2, v184
	s_addc_u32 s9, s9, 0
	v_ashrrev_i32_e32 v11, 31, v10
	v_mul_f32_e32 v2, 0x45800000, v0
	v_cndmask_b32_e32 v0, v0, v2, vcc
	v_add_u32_e32 v2, s4, v185
	v_ashrrev_i32_e32 v3, 31, v2
	v_lshlrev_b64 v[2:3], 11, v[2:3]
	v_lshl_add_u64 v[2:3], s[0:1], 0, v[2:3]
	s_mov_b32 s7, s56
	v_lshl_add_u64 v[6:7], v[10:11], 2, s[8:9]
	v_lshl_add_u64 v[8:9], v[2:3], 0, s[6:7]
	global_load_dwordx4 v[16:19], v[6:7], off
	global_load_dwordx4 v[20:23], v[6:7], off offset:32
	global_load_dwordx4 v[24:27], v[6:7], off offset:64
	global_load_dwordx4 v[28:31], v[6:7], off offset:96
	global_load_dwordx4 v[32:35], v[6:7], off offset:128
	global_load_dwordx4 v[36:39], v[6:7], off offset:160
	global_load_dwordx4 v[40:43], v[6:7], off offset:192
	global_load_dwordx4 v[44:47], v[6:7], off offset:224
	global_load_dwordx4 v[48:51], v[6:7], off offset:256
	global_load_dwordx4 v[52:55], v[6:7], off offset:288
	global_load_dwordx4 v[56:59], v[6:7], off offset:320
	global_load_dwordx4 v[60:63], v[6:7], off offset:352
	global_load_dwordx4 v[64:67], v[6:7], off offset:384
	global_load_dwordx4 v[68:71], v[6:7], off offset:416
	global_load_dwordx4 v[72:75], v[6:7], off offset:448
	global_load_dwordx4 v[76:79], v[6:7], off offset:480
	v_mul_f32_e32 v0, v239, v0
	s_waitcnt vmcnt(0)
	v_lshlrev_b32_e32 v218, 8, v185
	v_lshl_add_u32 v218, v185, 4, v218
	v_lshl_add_u32 v218, v184, 4, v218
	v_add_u32_e32 v218, s54, v218
	v_lshrrev_b32_e32 v220, 4, v194
	v_and_b32_e32 v221, 15, v194
	v_lshlrev_b32_e32 v219, 8, v220
	v_lshl_add_u32 v219, v220, 4, v219
	v_lshl_add_u32 v219, v221, 4, v219
	v_add_u32_e32 v219, s54, v219
	v_sub_u32_e32 v2, v220, v185
	v_ashrrev_i32_e32 v3, 31, v2
	v_lshlrev_b64 v[2:3], 11, v[2:3]
	v_lshl_add_u64 v[2:3], v[2:3], 0, v[8:9]
	v_lshlrev_b32_e32 v220, 4, v221
	v_mov_b32_e32 v221, 0
	v_lshl_add_u64 v[2:3], v[220:221], 0, v[2:3]
	v_pk_mul_f32 v[4:5], v[128:129], v[0:1] op_sel_hi:[1,0]
	v_pk_mul_f32 v[6:7], v[130:131], v[0:1] op_sel_hi:[1,0]
	v_pk_mul_f32 v[8:9], v[132:133], v[0:1] op_sel_hi:[1,0]
	v_pk_mul_f32 v[10:11], v[134:135], v[0:1] op_sel_hi:[1,0]
	v_pk_mul_f32 v[4:5], v[4:5], v[16:17]
	v_pk_mul_f32 v[6:7], v[6:7], v[18:19]
	v_pk_mul_f32 v[8:9], v[8:9], v[20:21]
	v_pk_mul_f32 v[10:11], v[10:11], v[22:23]
	v_cvt_pk_bf16_f32 v12, v4, v5
	v_cvt_pk_bf16_f32 v13, v6, v7
	v_cvt_pk_bf16_f32 v14, v8, v9
	v_cvt_pk_bf16_f32 v15, v10, v11
	s_nop 1
	v_permlane32_swap_b32_e32 v12, v14
	v_permlane32_swap_b32_e32 v13, v15
	ds_write_b128 v218, v[12:15]
	v_pk_mul_f32 v[4:5], v[136:137], v[0:1] op_sel_hi:[1,0]
	v_pk_mul_f32 v[6:7], v[138:139], v[0:1] op_sel_hi:[1,0]
	v_pk_mul_f32 v[8:9], v[140:141], v[0:1] op_sel_hi:[1,0]
	v_pk_mul_f32 v[10:11], v[142:143], v[0:1] op_sel_hi:[1,0]
	v_pk_mul_f32 v[4:5], v[4:5], v[24:25]
	v_pk_mul_f32 v[6:7], v[6:7], v[26:27]
	v_pk_mul_f32 v[8:9], v[8:9], v[28:29]
	v_pk_mul_f32 v[10:11], v[10:11], v[30:31]
	v_cvt_pk_bf16_f32 v12, v4, v5
	v_cvt_pk_bf16_f32 v13, v6, v7
	v_cvt_pk_bf16_f32 v14, v8, v9
	v_cvt_pk_bf16_f32 v15, v10, v11
	s_nop 1
	v_permlane32_swap_b32_e32 v12, v14
	v_permlane32_swap_b32_e32 v13, v15
	ds_write_b128 v218, v[12:15] offset:32
	v_pk_mul_f32 v[4:5], v[112:113], v[0:1] op_sel_hi:[1,0]
	v_pk_mul_f32 v[6:7], v[114:115], v[0:1] op_sel_hi:[1,0]
	v_pk_mul_f32 v[8:9], v[116:117], v[0:1] op_sel_hi:[1,0]
	v_pk_mul_f32 v[10:11], v[118:119], v[0:1] op_sel_hi:[1,0]
	v_pk_mul_f32 v[4:5], v[4:5], v[32:33]
	v_pk_mul_f32 v[6:7], v[6:7], v[34:35]
	v_pk_mul_f32 v[8:9], v[8:9], v[36:37]
	v_pk_mul_f32 v[10:11], v[10:11], v[38:39]
	v_cvt_pk_bf16_f32 v12, v4, v5
	v_cvt_pk_bf16_f32 v13, v6, v7
	v_cvt_pk_bf16_f32 v14, v8, v9
	v_cvt_pk_bf16_f32 v15, v10, v11
	s_nop 1
	v_permlane32_swap_b32_e32 v12, v14
	v_permlane32_swap_b32_e32 v13, v15
	ds_write_b128 v218, v[12:15] offset:64
	v_pk_mul_f32 v[4:5], v[120:121], v[0:1] op_sel_hi:[1,0]
	v_pk_mul_f32 v[6:7], v[122:123], v[0:1] op_sel_hi:[1,0]
	v_pk_mul_f32 v[8:9], v[124:125], v[0:1] op_sel_hi:[1,0]
	v_pk_mul_f32 v[10:11], v[126:127], v[0:1] op_sel_hi:[1,0]
	v_pk_mul_f32 v[4:5], v[4:5], v[40:41]
	v_pk_mul_f32 v[6:7], v[6:7], v[42:43]
	v_pk_mul_f32 v[8:9], v[8:9], v[44:45]
	v_pk_mul_f32 v[10:11], v[10:11], v[46:47]
	v_cvt_pk_bf16_f32 v12, v4, v5
	v_cvt_pk_bf16_f32 v13, v6, v7
	v_cvt_pk_bf16_f32 v14, v8, v9
	v_cvt_pk_bf16_f32 v15, v10, v11
	s_nop 1
	v_permlane32_swap_b32_e32 v12, v14
	v_permlane32_swap_b32_e32 v13, v15
	ds_write_b128 v218, v[12:15] offset:96
	v_pk_mul_f32 v[4:5], v[96:97], v[0:1] op_sel_hi:[1,0]
	v_pk_mul_f32 v[6:7], v[98:99], v[0:1] op_sel_hi:[1,0]
	v_pk_mul_f32 v[8:9], v[100:101], v[0:1] op_sel_hi:[1,0]
	v_pk_mul_f32 v[10:11], v[102:103], v[0:1] op_sel_hi:[1,0]
	v_pk_mul_f32 v[4:5], v[4:5], v[48:49]
	v_pk_mul_f32 v[6:7], v[6:7], v[50:51]
	v_pk_mul_f32 v[8:9], v[8:9], v[52:53]
	v_pk_mul_f32 v[10:11], v[10:11], v[54:55]
	v_cvt_pk_bf16_f32 v12, v4, v5
	v_cvt_pk_bf16_f32 v13, v6, v7
	v_cvt_pk_bf16_f32 v14, v8, v9
	v_cvt_pk_bf16_f32 v15, v10, v11
	s_nop 1
	v_permlane32_swap_b32_e32 v12, v14
	v_permlane32_swap_b32_e32 v13, v15
	ds_write_b128 v218, v[12:15] offset:128
	v_pk_mul_f32 v[4:5], v[104:105], v[0:1] op_sel_hi:[1,0]
	v_pk_mul_f32 v[6:7], v[106:107], v[0:1] op_sel_hi:[1,0]
	v_pk_mul_f32 v[8:9], v[108:109], v[0:1] op_sel_hi:[1,0]
	v_pk_mul_f32 v[10:11], v[110:111], v[0:1] op_sel_hi:[1,0]
	v_pk_mul_f32 v[4:5], v[4:5], v[56:57]
	v_pk_mul_f32 v[6:7], v[6:7], v[58:59]
	v_pk_mul_f32 v[8:9], v[8:9], v[60:61]
	v_pk_mul_f32 v[10:11], v[10:11], v[62:63]
	v_cvt_pk_bf16_f32 v12, v4, v5
	v_cvt_pk_bf16_f32 v13, v6, v7
	v_cvt_pk_bf16_f32 v14, v8, v9
	v_cvt_pk_bf16_f32 v15, v10, v11
	s_nop 1
	v_permlane32_swap_b32_e32 v12, v14
	v_permlane32_swap_b32_e32 v13, v15
	ds_write_b128 v218, v[12:15] offset:160
	v_pk_mul_f32 v[4:5], v[80:81], v[0:1] op_sel_hi:[1,0]
	v_pk_mul_f32 v[6:7], v[82:83], v[0:1] op_sel_hi:[1,0]
	v_pk_mul_f32 v[8:9], v[84:85], v[0:1] op_sel_hi:[1,0]
	v_pk_mul_f32 v[10:11], v[86:87], v[0:1] op_sel_hi:[1,0]
	v_pk_mul_f32 v[4:5], v[4:5], v[64:65]
	v_pk_mul_f32 v[6:7], v[6:7], v[66:67]
	v_pk_mul_f32 v[8:9], v[8:9], v[68:69]
	v_pk_mul_f32 v[10:11], v[10:11], v[70:71]
	v_cvt_pk_bf16_f32 v12, v4, v5
	v_cvt_pk_bf16_f32 v13, v6, v7
	v_cvt_pk_bf16_f32 v14, v8, v9
	v_cvt_pk_bf16_f32 v15, v10, v11
	s_nop 1
	v_permlane32_swap_b32_e32 v12, v14
	v_permlane32_swap_b32_e32 v13, v15
	ds_write_b128 v218, v[12:15] offset:192
	v_pk_mul_f32 v[4:5], v[88:89], v[0:1] op_sel_hi:[1,0]
	v_pk_mul_f32 v[6:7], v[90:91], v[0:1] op_sel_hi:[1,0]
	v_pk_mul_f32 v[8:9], v[92:93], v[0:1] op_sel_hi:[1,0]
	v_pk_mul_f32 v[10:11], v[94:95], v[0:1] op_sel_hi:[1,0]
	v_pk_mul_f32 v[4:5], v[4:5], v[72:73]
	v_pk_mul_f32 v[6:7], v[6:7], v[74:75]
	v_pk_mul_f32 v[8:9], v[8:9], v[76:77]
	v_pk_mul_f32 v[10:11], v[10:11], v[78:79]
	v_cvt_pk_bf16_f32 v12, v4, v5
	v_cvt_pk_bf16_f32 v13, v6, v7
	v_cvt_pk_bf16_f32 v14, v8, v9
	v_cvt_pk_bf16_f32 v15, v10, v11
	s_nop 1
	v_permlane32_swap_b32_e32 v12, v14
	v_permlane32_swap_b32_e32 v13, v15
	ds_write_b128 v218, v[12:15] offset:224
	s_waitcnt lgkmcnt(0)
	ds_read_b128 v[16:19], v219
	ds_read_b128 v[20:23], v219 offset:1088
	ds_read_b128 v[24:27], v219 offset:2176
	ds_read_b128 v[28:31], v219 offset:3264
	ds_read_b128 v[32:35], v219 offset:4352
	ds_read_b128 v[36:39], v219 offset:5440
	ds_read_b128 v[40:43], v219 offset:6528
	ds_read_b128 v[44:47], v219 offset:7616
	s_mov_b64 vcc, 0x2000
	s_waitcnt lgkmcnt(7)
	global_store_dwordx4 v[2:3], v[16:19], off
	s_nop 0
	v_lshl_add_u64 v[2:3], vcc, 0, v[2:3]
	s_waitcnt lgkmcnt(6)
	global_store_dwordx4 v[2:3], v[20:23], off
	s_nop 0
	v_lshl_add_u64 v[2:3], vcc, 0, v[2:3]
	s_waitcnt lgkmcnt(5)
	global_store_dwordx4 v[2:3], v[24:27], off
	s_nop 0
	v_lshl_add_u64 v[2:3], vcc, 0, v[2:3]
	s_waitcnt lgkmcnt(4)
	global_store_dwordx4 v[2:3], v[28:31], off
	s_nop 0
	v_lshl_add_u64 v[2:3], vcc, 0, v[2:3]
	s_waitcnt lgkmcnt(3)
	global_store_dwordx4 v[2:3], v[32:35], off
	s_nop 0
	v_lshl_add_u64 v[2:3], vcc, 0, v[2:3]
	s_waitcnt lgkmcnt(2)
	global_store_dwordx4 v[2:3], v[36:39], off
	s_nop 0
	v_lshl_add_u64 v[2:3], vcc, 0, v[2:3]
	s_waitcnt lgkmcnt(1)
	global_store_dwordx4 v[2:3], v[40:43], off
	s_nop 0
	v_lshl_add_u64 v[2:3], vcc, 0, v[2:3]
	s_waitcnt lgkmcnt(0)
	global_store_dwordx4 v[2:3], v[44:47], off
